# part A prefetch depth 3 tokens (4 rotating raw buffers), rope 2 ahead
# baseline (speedup 1.0000x reference)
.LBB0_690:
	s_mov_b32 s56, 0x800000
	s_or_b64 exec, exec, s[4:5]
	s_mov_b64 s[4:5], s[66:67]
	v_mov_b32_e32 v0, v1
	s_waitcnt lgkmcnt(0)
	s_barrier
	s_load_dwordx4 s[48:51], s[4:5], 0xf8
	s_load_dwordx4 s[8:11], s[4:5], 0x80
	v_mbcnt_lo_u32_b32 v0, -1, v0
	v_mbcnt_hi_u32_b32 v0, -1, v0
	v_add_u32_e32 v2, s86, v0
	v_and_b32_e32 v58, 63, v0
	v_readfirstlane_b32 s0, v2
	s_nop 1
	v_writelane_b32 v255, s0, 36
	s_ashr_i32 s0, s0, 6
	s_add_i32 s1, s0, s55
	v_writelane_b32 v255, s0, 37
	s_waitcnt lgkmcnt(0)
	s_add_u32 s46, s50, 0x6c00000
	s_addc_u32 s47, s51, 0
	v_writelane_b32 v255, s8, 38
	s_add_u32 s58, s50, 0xd800000
	s_addc_u32 s59, s51, 0
	v_writelane_b32 v255, s9, 39
	v_writelane_b32 v255, s10, 40
	v_writelane_b32 v255, s11, 41
	s_cmpk_gt_i32 s1, 0x3fff
	s_cbranch_scc1 .LBB0_826
	s_load_dwordx4 s[24:27], s[66:67], 0xc8
	s_load_dwordx4 s[28:31], s[66:67], 0xe0
	v_readlane_b32 s5, v255, 21
	s_and_b32 s2, s1, 3
	s_lshr_b32 s3, s1, 2
	s_lshr_b32 s4, s68, 2
	s_mov_b32 s16, 0x3c800000
	v_lshrrev_b32_e32 v23, 3, v58
	s_lshl_b32 s0, s2, 3
	v_add_u32_e32 v23, s0, v23
	v_and_b32_e32 v59, 7, v58
	v_add_u32_e32 v66, -20, v23
	v_cmp_gt_u32_e64 s[6:7], 8, v66
	s_nop 1
	v_add_u32_e32 v66, -12, v23
	v_cmp_gt_u32_e64 s[8:9], 6, v66
	s_nop 1
	v_add_u32_e32 v66, -26, v23
	v_cmp_gt_u32_e64 s[10:11], 2, v66
	s_nop 1
	v_add_u32_e32 v66, -28, v23
	v_cmp_gt_u32_e64 s[12:13], 4, v66
	s_nop 1
	s_nop 3
	s_or_b64 s[10:11], s[8:9], s[10:11]
	s_or_b64 s[8:9], s[10:11], s[12:13]
	s_not_b64 s[8:9], s[8:9]
	s_mov_b64 s[12:13], s[8:9]
	v_add_u32_e32 v66, -6, v23
	v_cmp_gt_u32_e64 s[14:15], 6, v66
	s_nop 1
	v_add_u32_e32 v66, -24, v23
	v_cmp_gt_u32_e64 s[20:21], 2, v66
	s_nop 1
	s_nop 3
	s_or_b64 s[14:15], s[14:15], s[20:21]
	s_or_b64 s[10:11], s[10:11], s[14:15]
	v_add_u32_e32 v66, -18, v23
	v_cmp_gt_u32_e64 s[14:15], 8, v66
	s_nop 1
	s_nop 3
	v_mov_b32_e32 v17, 1.0
	v_cmp_gt_u32_e32 vcc, 6, v23
	s_nop 1
	v_mov_b32_e32 v67, 0x3e000000
	v_cndmask_b32_e32 v17, v17, v67, vcc
	v_add_u32_e32 v66, -18, v23
	v_cmp_gt_u32_e32 vcc, 6, v66
	s_nop 1
	v_mov_b32_e32 v67, 0x3e000000
	v_cndmask_b32_e32 v17, v17, v67, vcc
	v_and_b32_e32 v66, 2, v59
	v_cmp_eq_u32_e32 vcc, 0, v66
	s_nop 1
	v_mov_b32_e32 v67, 0x80000000
	v_cndmask_b32_e32 v22, 0, v67, vcc
	v_and_b32_e32 v66, 1, v59
	v_lshlrev_b32_e32 v21, 6, v66
	v_and_b32_e32 v66, 4, v59
	v_lshl_add_u32 v21, v66, 5, v21
	v_lshlrev_b32_e32 v65, 4, v59
	v_mov_b32_e32 v0, 0
	v_mov_b32_e32 v64, 0
	v_cmp_gt_u32_e32 vcc, 20, v23
	s_nop 1
	s_mov_b32 s0, 0x6c00600
	v_lshl_add_u32 v67, v23, 7, s0
	v_cndmask_b32_e32 v64, v64, v67, vcc
	v_add_u32_e32 v66, -20, v23
	v_cmp_gt_u32_e32 vcc, 8, v66
	s_nop 1
	s_mov_b32 s0, 0xd800000
	v_lshl_add_u32 v67, v66, 7, s0
	v_cndmask_b32_e32 v64, v64, v67, vcc
	v_add_u32_e32 v66, -28, v23
	v_cmp_gt_u32_e32 vcc, 4, v66
	s_nop 1
	s_mov_b32 s0, 0x6c00600
	v_lshl_add_u32 v67, v66, 7, s0
	v_cndmask_b32_e32 v64, v64, v67, vcc
	v_add_u32_e32 v64, v64, v65
	v_mov_b32_e32 v65, 0
	v_lshl_add_u64 v[2:3], s[50:51], 0, v[64:65]
	v_mov_b32_e32 v4, 0x1400
	v_add_u32_e32 v66, -20, v23
	v_cmp_gt_u32_e32 vcc, 8, v66
	s_nop 1
	v_mov_b32_e32 v67, 0x400
	v_cndmask_b32_e32 v4, v4, v67, vcc
	v_mov_b32_e32 v5, 0
	v_add_u32_e32 v66, -20, v23
	v_cmp_gt_u32_e32 vcc, 8, v66
	s_nop 1
	v_mov_b32_e32 v67, 0x800000
	v_cndmask_b32_e32 v5, v5, v67, vcc
	v_lshlrev_b32_e32 v63, 4, v59
	v_mov_b32_e32 v64, 0x9800000
	v_cmp_gt_u32_e32 vcc, 6, v23
	s_nop 1
	s_mov_b32 s0, 0x9800000
	v_lshl_add_u32 v67, v23, 7, s0
	v_cndmask_b32_e32 v64, v64, v67, vcc
	v_add_u32_e32 v66, -6, v23
	v_cmp_gt_u32_e32 vcc, 6, v66
	s_nop 1
	s_mov_b32 s0, 0x9e00000
	v_lshl_add_u32 v67, v66, 7, s0
	v_cndmask_b32_e32 v64, v64, v67, vcc
	v_add_u32_e32 v66, -18, v23
	v_cmp_gt_u32_e32 vcc, 6, v66
	s_nop 1
	s_mov_b32 s0, 0xaa00000
	v_lshl_add_u32 v67, v66, 7, s0
	v_cndmask_b32_e32 v64, v64, v67, vcc
	v_add_u32_e32 v66, -24, v23
	v_cmp_gt_u32_e32 vcc, 2, v66
	s_nop 1
	s_mov_b32 s0, 0xb000000
	v_lshl_add_u32 v67, v66, 7, s0
	v_cndmask_b32_e32 v64, v64, v67, vcc
	v_add_u32_e32 v64, v64, v63
	v_mov_b32_e32 v65, 0
	v_lshl_add_u64 v[14:15], s[50:51], 0, v[64:65]
	v_mov_b32_e32 v16, 0x300
	v_add_u32_e32 v66, -24, v23
	v_cmp_gt_u32_e32 vcc, 2, v66
	s_nop 1
	v_mov_b32_e32 v67, 0x100
	v_cndmask_b32_e32 v16, v16, v67, vcc
	v_lshlrev_b32_e32 v63, 5, v59
	v_mov_b32_e32 v64, 0x2000000
	v_add_u32_e32 v66, -6, v23
	v_cmp_gt_u32_e32 vcc, 6, v66
	s_nop 1
	s_mov_b32 s0, 0x2000000
	v_lshl_add_u32 v67, v66, 8, s0
	v_cndmask_b32_e32 v64, v64, v67, vcc
	v_add_u32_e32 v66, -12, v23
	v_cmp_gt_u32_e32 vcc, 6, v66
	s_nop 1
	s_mov_b32 s0, 0x2c00000
	v_lshl_add_u32 v67, v66, 8, s0
	v_cndmask_b32_e32 v64, v64, v67, vcc
	v_add_u32_e32 v66, -24, v23
	v_cmp_gt_u32_e32 vcc, 2, v66
	s_nop 1
	s_mov_b32 s0, 0x3800000
	v_lshl_add_u32 v67, v66, 8, s0
	v_cndmask_b32_e32 v64, v64, v67, vcc
	v_add_u32_e32 v66, -26, v23
	v_cmp_gt_u32_e32 vcc, 2, v66
	s_nop 1
	s_mov_b32 s0, 0x3c00000
	v_lshl_add_u32 v67, v66, 8, s0
	v_cndmask_b32_e32 v64, v64, v67, vcc
	v_add_u32_e32 v64, v64, v63
	v_mov_b32_e32 v65, 0
	v_lshl_add_u64 v[18:19], s[48:49], 0, v[64:65]
	v_mov_b32_e32 v20, 0x600
	v_add_u32_e32 v66, -24, v23
	v_cmp_gt_u32_e32 vcc, 4, v66
	s_nop 1
	v_mov_b32_e32 v67, 0x200
	v_cndmask_b32_e32 v20, v20, v67, vcc
	s_waitcnt lgkmcnt(0)
	s_lshl_b32 s0, s5, 8
	s_add_u32 s24, s24, s0
	s_addc_u32 s25, s25, 0
	s_add_u32 s26, s26, s0
	s_addc_u32 s27, s27, 0
	s_add_u32 s28, s28, s0
	s_addc_u32 s29, s29, 0
	s_add_u32 s30, s30, s0
	s_addc_u32 s31, s31, 0
	v_mov_b32_e32 v60, s24
	v_mov_b32_e32 v61, s25
	v_add_u32_e32 v66, -6, v23
	v_cmp_gt_u32_e32 vcc, 6, v66
	s_nop 1
	v_mov_b32_e32 v66, s26
	v_mov_b32_e32 v67, s27
	v_cndmask_b32_e32 v60, v60, v66, vcc
	v_cndmask_b32_e32 v61, v61, v67, vcc
	v_add_u32_e32 v66, -18, v23
	v_cmp_gt_u32_e32 vcc, 6, v66
	s_nop 1
	v_mov_b32_e32 v66, s28
	v_mov_b32_e32 v67, s29
	v_cndmask_b32_e32 v60, v60, v66, vcc
	v_cndmask_b32_e32 v61, v61, v67, vcc
	v_add_u32_e32 v66, -24, v23
	v_cmp_gt_u32_e32 vcc, 2, v66
	s_nop 1
	v_mov_b32_e32 v66, s30
	v_mov_b32_e32 v67, s31
	v_cndmask_b32_e32 v60, v60, v66, vcc
	v_cndmask_b32_e32 v61, v61, v67, vcc
	v_lshlrev_b32_e32 v64, 5, v59
	v_mov_b32_e32 v65, 0
	v_lshl_add_u64 v[60:61], v[60:61], 0, v[64:65]
	global_load_dwordx4 v[6:9], v[60:61], off
	global_load_dwordx4 v[10:13], v[60:61], off offset:16
	s_add_u32 s18, s50, 0x5080000
	s_addc_u32 s19, s51, 0
	s_waitcnt vmcnt(0)
	v_mad_u64_u32 v[56:57], s[26:27], s3, v4, v[2:3]
	v_mov_b32_e32 v66, 0
	v_add_co_u32_e32 v60, vcc, v56, v5
	s_nop 1
	v_addc_co_u32_e32 v61, vcc, v57, v66, vcc
	global_load_dwordx4 v[28:31], v[60:61], off
	global_load_dwordx4 v[24:27], v[56:57], off
	s_mul_i32 s17, s4, 1
	s_add_i32 s17, s17, s3
	s_min_u32 s17, s17, 0x1fff
	v_mad_u64_u32 v[56:57], s[26:27], s17, v4, v[2:3]
	v_mov_b32_e32 v66, 0
	v_add_co_u32_e32 v60, vcc, v56, v5
	s_nop 1
	v_addc_co_u32_e32 v61, vcc, v57, v66, vcc
	global_load_dwordx4 v[72:75], v[60:61], off
	global_load_dwordx4 v[68:71], v[56:57], off
	s_mul_i32 s17, s4, 2
	s_add_i32 s17, s17, s3
	s_min_u32 s17, s17, 0x1fff
	v_mad_u64_u32 v[56:57], s[26:27], s17, v4, v[2:3]
	v_mov_b32_e32 v66, 0
	v_add_co_u32_e32 v60, vcc, v56, v5
	s_nop 1
	v_addc_co_u32_e32 v61, vcc, v57, v66, vcc
	global_load_dwordx4 v[80:83], v[60:61], off
	global_load_dwordx4 v[76:79], v[56:57], off
	s_waitcnt vmcnt(0)
	s_cmpk_lt_u32 s3, 0x1000
	s_cbranch_scc0 .Lpa_ctx_done
	s_branch .Lpa_ctx_b0
.Lpa_ctx_t0:
	s_waitcnt vmcnt(13)
.Lpa_ctx_b0:
	v_lshlrev_b32_e32 v32, 16, v24
	v_and_b32_e32 v33, s85, v24
	v_lshlrev_b32_e32 v34, 16, v25
	v_and_b32_e32 v35, s85, v25
	v_lshlrev_b32_e32 v36, 16, v26
	v_and_b32_e32 v37, s85, v26
	v_lshlrev_b32_e32 v38, 16, v27
	v_and_b32_e32 v39, s85, v27
	s_mov_b64 exec, s[6:7]
	v_lshlrev_b32_e32 v66, 16, v28
	v_and_b32_e32 v67, s85, v28
	v_add_f32_e32 v32, v32, v66
	v_add_f32_e32 v33, v33, v67
	v_lshlrev_b32_e32 v66, 16, v29
	v_and_b32_e32 v67, s85, v29
	v_add_f32_e32 v34, v34, v66
	v_add_f32_e32 v35, v35, v67
	v_lshlrev_b32_e32 v66, 16, v30
	v_and_b32_e32 v67, s85, v30
	v_add_f32_e32 v36, v36, v66
	v_add_f32_e32 v37, v37, v67
	v_lshlrev_b32_e32 v66, 16, v31
	v_and_b32_e32 v67, s85, v31
	v_add_f32_e32 v38, v38, v66
	v_add_f32_e32 v39, v39, v67
	s_mov_b64 exec, -1
	s_mul_i32 s17, s4, 3
	s_add_i32 s17, s17, s3
	s_min_u32 s17, s17, 0x1fff
	v_mad_u64_u32 v[56:57], s[26:27], s17, v4, v[2:3]
	v_mov_b32_e32 v66, 0
	v_add_co_u32_e32 v60, vcc, v56, v5
	s_nop 1
	v_addc_co_u32_e32 v61, vcc, v57, v66, vcc
	global_load_dwordx4 v[88:91], v[60:61], off
	global_load_dwordx4 v[84:87], v[56:57], off
	v_mul_f32_e32 v66, v32, v32
	v_fmac_f32_e32 v66, v33, v33
	v_fmac_f32_e32 v66, v34, v34
	v_fmac_f32_e32 v66, v35, v35
	v_fmac_f32_e32 v66, v36, v36
	v_fmac_f32_e32 v66, v37, v37
	v_fmac_f32_e32 v66, v38, v38
	v_fmac_f32_e32 v66, v39, v39
	s_nop 1
	v_add_f32_dpp v66, v66, v66 quad_perm:[1,0,3,2] row_mask:0xf bank_mask:0xf
	s_nop 1
	v_add_f32_dpp v66, v66, v66 quad_perm:[2,3,0,1] row_mask:0xf bank_mask:0xf
	s_nop 1
	v_add_f32_dpp v66, v66, v66 row_half_mirror row_mask:0xf bank_mask:0xf
	v_mov_b32_e32 v67, 0x358637bd
	v_fmac_f32_e32 v67, s16, v66
	v_rsq_f32_e32 v67, v67
	s_mov_b64 exec, s[8:9]
	v_mul_f32_e32 v32, v32, v67
	v_mul_f32_e32 v33, v33, v67
	v_mul_f32_e32 v34, v34, v67
	v_mul_f32_e32 v35, v35, v67
	v_mul_f32_e32 v36, v36, v67
	v_mul_f32_e32 v37, v37, v67
	v_mul_f32_e32 v38, v38, v67
	v_mul_f32_e32 v39, v39, v67
	v_mul_f32_e32 v32, v32, v6
	v_mul_f32_e32 v33, v33, v7
	v_mul_f32_e32 v34, v34, v8
	v_mul_f32_e32 v35, v35, v9
	v_mul_f32_e32 v36, v36, v10
	v_mul_f32_e32 v37, v37, v11
	v_mul_f32_e32 v38, v38, v12
	v_mul_f32_e32 v39, v39, v13
	s_mov_b64 exec, -1
	s_lshr_b32 s22, s3, 8
	s_lshl_b32 s22, s22, 1
	s_add_i32 s22, s22, s5
	s_lshl_b32 s22, s22, 8
	s_and_b32 s0, s3, 0xff
	s_add_i32 s22, s22, s0
	v_mad_u64_u32 v[60:61], s[26:27], s22, v20, v[18:19]
	s_mov_b64 exec, s[10:11]
	global_store_dwordx4 v[60:61], v[32:35], off
	global_store_dwordx4 v[60:61], v[36:39], off offset:16
	s_mov_b64 exec, -1
	v_mul_f32_e32 v32, v32, v17
	v_mul_f32_e32 v33, v33, v17
	v_mul_f32_e32 v34, v34, v17
	v_mul_f32_e32 v35, v35, v17
	v_mul_f32_e32 v36, v36, v17
	v_mul_f32_e32 v37, v37, v17
	v_mul_f32_e32 v38, v38, v17
	v_mul_f32_e32 v39, v39, v17
	v_cvt_pk_bf16_f32 v62, v32, v33
	v_cvt_pk_bf16_f32 v63, v34, v35
	v_cvt_pk_bf16_f32 v64, v36, v37
	v_cvt_pk_bf16_f32 v65, v38, v39
	v_mad_u64_u32 v[56:57], s[26:27], s3, v16, v[14:15]
	s_mov_b64 exec, s[12:13]
	global_store_dwordx4 v[56:57], v[62:65], off
	s_mov_b64 exec, -1
	s_add_i32 s3, s3, s4
	s_cmpk_lt_u32 s3, 0x1000
	s_cbranch_scc0 .Lpa_ctx_done0

.Lpa_ctx_b1:
	v_lshlrev_b32_e32 v32, 16, v68
	v_and_b32_e32 v33, s85, v68
	v_lshlrev_b32_e32 v34, 16, v69
	v_and_b32_e32 v35, s85, v69
	v_lshlrev_b32_e32 v36, 16, v70
	v_and_b32_e32 v37, s85, v70
	v_lshlrev_b32_e32 v38, 16, v71
	v_and_b32_e32 v39, s85, v71
	s_mov_b64 exec, s[6:7]
	v_lshlrev_b32_e32 v66, 16, v72
	v_and_b32_e32 v67, s85, v72
	v_add_f32_e32 v32, v32, v66
	v_add_f32_e32 v33, v33, v67
	v_lshlrev_b32_e32 v66, 16, v73
	v_and_b32_e32 v67, s85, v73
	v_add_f32_e32 v34, v34, v66
	v_add_f32_e32 v35, v35, v67
	v_lshlrev_b32_e32 v66, 16, v74
	v_and_b32_e32 v67, s85, v74
	v_add_f32_e32 v36, v36, v66
	v_add_f32_e32 v37, v37, v67
	v_lshlrev_b32_e32 v66, 16, v75
	v_and_b32_e32 v67, s85, v75
	v_add_f32_e32 v38, v38, v66
	v_add_f32_e32 v39, v39, v67
	s_mov_b64 exec, -1
	s_mul_i32 s17, s4, 3
	s_add_i32 s17, s17, s3
	s_min_u32 s17, s17, 0x1fff
	v_mad_u64_u32 v[56:57], s[26:27], s17, v4, v[2:3]
	v_mov_b32_e32 v66, 0
	v_add_co_u32_e32 v60, vcc, v56, v5
	s_nop 1
	v_addc_co_u32_e32 v61, vcc, v57, v66, vcc
	global_load_dwordx4 v[28:31], v[60:61], off
	global_load_dwordx4 v[24:27], v[56:57], off
	v_mul_f32_e32 v66, v32, v32
	v_fmac_f32_e32 v66, v33, v33
	v_fmac_f32_e32 v66, v34, v34
	v_fmac_f32_e32 v66, v35, v35
	v_fmac_f32_e32 v66, v36, v36
	v_fmac_f32_e32 v66, v37, v37
	v_fmac_f32_e32 v66, v38, v38
	v_fmac_f32_e32 v66, v39, v39
	s_nop 1
	v_add_f32_dpp v66, v66, v66 quad_perm:[1,0,3,2] row_mask:0xf bank_mask:0xf
	s_nop 1
	v_add_f32_dpp v66, v66, v66 quad_perm:[2,3,0,1] row_mask:0xf bank_mask:0xf
	s_nop 1
	v_add_f32_dpp v66, v66, v66 row_half_mirror row_mask:0xf bank_mask:0xf
	v_mov_b32_e32 v67, 0x358637bd
	v_fmac_f32_e32 v67, s16, v66
	v_rsq_f32_e32 v67, v67
	s_mov_b64 exec, s[8:9]
	v_mul_f32_e32 v32, v32, v67
	v_mul_f32_e32 v33, v33, v67
	v_mul_f32_e32 v34, v34, v67
	v_mul_f32_e32 v35, v35, v67
	v_mul_f32_e32 v36, v36, v67
	v_mul_f32_e32 v37, v37, v67
	v_mul_f32_e32 v38, v38, v67
	v_mul_f32_e32 v39, v39, v67
	v_mul_f32_e32 v32, v32, v6
	v_mul_f32_e32 v33, v33, v7
	v_mul_f32_e32 v34, v34, v8
	v_mul_f32_e32 v35, v35, v9
	v_mul_f32_e32 v36, v36, v10
	v_mul_f32_e32 v37, v37, v11
	v_mul_f32_e32 v38, v38, v12
	v_mul_f32_e32 v39, v39, v13
	s_mov_b64 exec, -1
	s_lshr_b32 s22, s3, 8
	s_lshl_b32 s22, s22, 1
	s_add_i32 s22, s22, s5
	s_lshl_b32 s22, s22, 8
	s_and_b32 s0, s3, 0xff
	s_add_i32 s22, s22, s0
	v_mad_u64_u32 v[60:61], s[26:27], s22, v20, v[18:19]
	s_mov_b64 exec, s[10:11]
	global_store_dwordx4 v[60:61], v[32:35], off
	global_store_dwordx4 v[60:61], v[36:39], off offset:16
	s_mov_b64 exec, -1
	v_mul_f32_e32 v32, v32, v17
	v_mul_f32_e32 v33, v33, v17
	v_mul_f32_e32 v34, v34, v17
	v_mul_f32_e32 v35, v35, v17
	v_mul_f32_e32 v36, v36, v17
	v_mul_f32_e32 v37, v37, v17
	v_mul_f32_e32 v38, v38, v17
	v_mul_f32_e32 v39, v39, v17
	v_cvt_pk_bf16_f32 v62, v32, v33
	v_cvt_pk_bf16_f32 v63, v34, v35
	v_cvt_pk_bf16_f32 v64, v36, v37
	v_cvt_pk_bf16_f32 v65, v38, v39
	v_mad_u64_u32 v[56:57], s[26:27], s3, v16, v[14:15]
	s_mov_b64 exec, s[12:13]
	global_store_dwordx4 v[56:57], v[62:65], off
	s_mov_b64 exec, -1
	s_add_i32 s3, s3, s4
	s_cmpk_lt_u32 s3, 0x1000
	s_cbranch_scc0 .Lpa_ctx_done1

.Lpa_ctx_b2:
	v_lshlrev_b32_e32 v32, 16, v76
	v_and_b32_e32 v33, s85, v76
	v_lshlrev_b32_e32 v34, 16, v77
	v_and_b32_e32 v35, s85, v77
	v_lshlrev_b32_e32 v36, 16, v78
	v_and_b32_e32 v37, s85, v78
	v_lshlrev_b32_e32 v38, 16, v79
	v_and_b32_e32 v39, s85, v79
	s_mov_b64 exec, s[6:7]
	v_lshlrev_b32_e32 v66, 16, v80
	v_and_b32_e32 v67, s85, v80
	v_add_f32_e32 v32, v32, v66
	v_add_f32_e32 v33, v33, v67
	v_lshlrev_b32_e32 v66, 16, v81
	v_and_b32_e32 v67, s85, v81
	v_add_f32_e32 v34, v34, v66
	v_add_f32_e32 v35, v35, v67
	v_lshlrev_b32_e32 v66, 16, v82
	v_and_b32_e32 v67, s85, v82
	v_add_f32_e32 v36, v36, v66
	v_add_f32_e32 v37, v37, v67
	v_lshlrev_b32_e32 v66, 16, v83
	v_and_b32_e32 v67, s85, v83
	v_add_f32_e32 v38, v38, v66
	v_add_f32_e32 v39, v39, v67
	s_mov_b64 exec, -1
	s_mul_i32 s17, s4, 3
	s_add_i32 s17, s17, s3
	s_min_u32 s17, s17, 0x1fff
	v_mad_u64_u32 v[56:57], s[26:27], s17, v4, v[2:3]
	v_mov_b32_e32 v66, 0
	v_add_co_u32_e32 v60, vcc, v56, v5
	s_nop 1
	v_addc_co_u32_e32 v61, vcc, v57, v66, vcc
	global_load_dwordx4 v[72:75], v[60:61], off
	global_load_dwordx4 v[68:71], v[56:57], off
	v_mul_f32_e32 v66, v32, v32
	v_fmac_f32_e32 v66, v33, v33
	v_fmac_f32_e32 v66, v34, v34
	v_fmac_f32_e32 v66, v35, v35
	v_fmac_f32_e32 v66, v36, v36
	v_fmac_f32_e32 v66, v37, v37
	v_fmac_f32_e32 v66, v38, v38
	v_fmac_f32_e32 v66, v39, v39
	s_nop 1
	v_add_f32_dpp v66, v66, v66 quad_perm:[1,0,3,2] row_mask:0xf bank_mask:0xf
	s_nop 1
	v_add_f32_dpp v66, v66, v66 quad_perm:[2,3,0,1] row_mask:0xf bank_mask:0xf
	s_nop 1
	v_add_f32_dpp v66, v66, v66 row_half_mirror row_mask:0xf bank_mask:0xf
	v_mov_b32_e32 v67, 0x358637bd
	v_fmac_f32_e32 v67, s16, v66
	v_rsq_f32_e32 v67, v67
	s_mov_b64 exec, s[8:9]
	v_mul_f32_e32 v32, v32, v67
	v_mul_f32_e32 v33, v33, v67
	v_mul_f32_e32 v34, v34, v67
	v_mul_f32_e32 v35, v35, v67
	v_mul_f32_e32 v36, v36, v67
	v_mul_f32_e32 v37, v37, v67
	v_mul_f32_e32 v38, v38, v67
	v_mul_f32_e32 v39, v39, v67
	v_mul_f32_e32 v32, v32, v6
	v_mul_f32_e32 v33, v33, v7
	v_mul_f32_e32 v34, v34, v8
	v_mul_f32_e32 v35, v35, v9
	v_mul_f32_e32 v36, v36, v10
	v_mul_f32_e32 v37, v37, v11
	v_mul_f32_e32 v38, v38, v12
	v_mul_f32_e32 v39, v39, v13
	s_mov_b64 exec, -1
	s_lshr_b32 s22, s3, 8
	s_lshl_b32 s22, s22, 1
	s_add_i32 s22, s22, s5
	s_lshl_b32 s22, s22, 8
	s_and_b32 s0, s3, 0xff
	s_add_i32 s22, s22, s0
	v_mad_u64_u32 v[60:61], s[26:27], s22, v20, v[18:19]
	s_mov_b64 exec, s[10:11]
	global_store_dwordx4 v[60:61], v[32:35], off
	global_store_dwordx4 v[60:61], v[36:39], off offset:16
	s_mov_b64 exec, -1
	v_mul_f32_e32 v32, v32, v17
	v_mul_f32_e32 v33, v33, v17
	v_mul_f32_e32 v34, v34, v17
	v_mul_f32_e32 v35, v35, v17
	v_mul_f32_e32 v36, v36, v17
	v_mul_f32_e32 v37, v37, v17
	v_mul_f32_e32 v38, v38, v17
	v_mul_f32_e32 v39, v39, v17
	v_cvt_pk_bf16_f32 v62, v32, v33
	v_cvt_pk_bf16_f32 v63, v34, v35
	v_cvt_pk_bf16_f32 v64, v36, v37
	v_cvt_pk_bf16_f32 v65, v38, v39
	v_mad_u64_u32 v[56:57], s[26:27], s3, v16, v[14:15]
	s_mov_b64 exec, s[12:13]
	global_store_dwordx4 v[56:57], v[62:65], off
	s_mov_b64 exec, -1
	s_add_i32 s3, s3, s4
	s_cmpk_lt_u32 s3, 0x1000
	s_cbranch_scc0 .Lpa_ctx_done2

.Lpa_ctx_b3:
	v_lshlrev_b32_e32 v32, 16, v84
	v_and_b32_e32 v33, s85, v84
	v_lshlrev_b32_e32 v34, 16, v85
	v_and_b32_e32 v35, s85, v85
	v_lshlrev_b32_e32 v36, 16, v86
	v_and_b32_e32 v37, s85, v86
	v_lshlrev_b32_e32 v38, 16, v87
	v_and_b32_e32 v39, s85, v87
	s_mov_b64 exec, s[6:7]
	v_lshlrev_b32_e32 v66, 16, v88
	v_and_b32_e32 v67, s85, v88
	v_add_f32_e32 v32, v32, v66
	v_add_f32_e32 v33, v33, v67
	v_lshlrev_b32_e32 v66, 16, v89
	v_and_b32_e32 v67, s85, v89
	v_add_f32_e32 v34, v34, v66
	v_add_f32_e32 v35, v35, v67
	v_lshlrev_b32_e32 v66, 16, v90
	v_and_b32_e32 v67, s85, v90
	v_add_f32_e32 v36, v36, v66
	v_add_f32_e32 v37, v37, v67
	v_lshlrev_b32_e32 v66, 16, v91
	v_and_b32_e32 v67, s85, v91
	v_add_f32_e32 v38, v38, v66
	v_add_f32_e32 v39, v39, v67
	s_mov_b64 exec, -1
	s_mul_i32 s17, s4, 3
	s_add_i32 s17, s17, s3
	s_min_u32 s17, s17, 0x1fff
	v_mad_u64_u32 v[56:57], s[26:27], s17, v4, v[2:3]
	v_mov_b32_e32 v66, 0
	v_add_co_u32_e32 v60, vcc, v56, v5
	s_nop 1
	v_addc_co_u32_e32 v61, vcc, v57, v66, vcc
	global_load_dwordx4 v[80:83], v[60:61], off
	global_load_dwordx4 v[76:79], v[56:57], off
	v_mul_f32_e32 v66, v32, v32
	v_fmac_f32_e32 v66, v33, v33
	v_fmac_f32_e32 v66, v34, v34
	v_fmac_f32_e32 v66, v35, v35
	v_fmac_f32_e32 v66, v36, v36
	v_fmac_f32_e32 v66, v37, v37
	v_fmac_f32_e32 v66, v38, v38
	v_fmac_f32_e32 v66, v39, v39
	s_nop 1
	v_add_f32_dpp v66, v66, v66 quad_perm:[1,0,3,2] row_mask:0xf bank_mask:0xf
	s_nop 1
	v_add_f32_dpp v66, v66, v66 quad_perm:[2,3,0,1] row_mask:0xf bank_mask:0xf
	s_nop 1
	v_add_f32_dpp v66, v66, v66 row_half_mirror row_mask:0xf bank_mask:0xf
	v_mov_b32_e32 v67, 0x358637bd
	v_fmac_f32_e32 v67, s16, v66
	v_rsq_f32_e32 v67, v67
	s_mov_b64 exec, s[8:9]
	v_mul_f32_e32 v32, v32, v67
	v_mul_f32_e32 v33, v33, v67
	v_mul_f32_e32 v34, v34, v67
	v_mul_f32_e32 v35, v35, v67
	v_mul_f32_e32 v36, v36, v67
	v_mul_f32_e32 v37, v37, v67
	v_mul_f32_e32 v38, v38, v67
	v_mul_f32_e32 v39, v39, v67
	v_mul_f32_e32 v32, v32, v6
	v_mul_f32_e32 v33, v33, v7
	v_mul_f32_e32 v34, v34, v8
	v_mul_f32_e32 v35, v35, v9
	v_mul_f32_e32 v36, v36, v10
	v_mul_f32_e32 v37, v37, v11
	v_mul_f32_e32 v38, v38, v12
	v_mul_f32_e32 v39, v39, v13
	s_mov_b64 exec, -1
	s_lshr_b32 s22, s3, 8
	s_lshl_b32 s22, s22, 1
	s_add_i32 s22, s22, s5
	s_lshl_b32 s22, s22, 8
	s_and_b32 s0, s3, 0xff
	s_add_i32 s22, s22, s0
	v_mad_u64_u32 v[60:61], s[26:27], s22, v20, v[18:19]
	s_mov_b64 exec, s[10:11]
	global_store_dwordx4 v[60:61], v[32:35], off
	global_store_dwordx4 v[60:61], v[36:39], off offset:16
	s_mov_b64 exec, -1
	v_mul_f32_e32 v32, v32, v17
	v_mul_f32_e32 v33, v33, v17
	v_mul_f32_e32 v34, v34, v17
	v_mul_f32_e32 v35, v35, v17
	v_mul_f32_e32 v36, v36, v17
	v_mul_f32_e32 v37, v37, v17
	v_mul_f32_e32 v38, v38, v17
	v_mul_f32_e32 v39, v39, v17
	v_cvt_pk_bf16_f32 v62, v32, v33
	v_cvt_pk_bf16_f32 v63, v34, v35
	v_cvt_pk_bf16_f32 v64, v36, v37
	v_cvt_pk_bf16_f32 v65, v38, v39
	v_mad_u64_u32 v[56:57], s[26:27], s3, v16, v[14:15]
	s_mov_b64 exec, s[12:13]
	global_store_dwordx4 v[56:57], v[62:65], off
	s_mov_b64 exec, -1
	s_add_i32 s3, s3, s4
	s_cmpk_lt_u32 s3, 0x1000
	s_cbranch_scc1 .Lpa_ctx_t0
	s_branch .Lpa_ctx_done3
.Lpa_ctx_done0:
	s_branch .Lpa_lat_entry1

.Lpa_lat_entry0:
	s_cmpk_lt_u32 s3, 0x2000
	s_cbranch_scc0 .Lpa_done
	s_and_b32 s0, s3, 0x7ff
	s_lshl_b32 s0, s0, 8
	s_add_u32 s20, s18, s0
	s_addc_u32 s21, s19, 0
	global_load_dwordx4 v[40:43], v21, s[20:21]
	global_load_dwordx4 v[44:47], v21, s[20:21] offset:16
	global_load_dwordx4 v[48:51], v21, s[20:21] offset:32
	global_load_dwordx4 v[52:55], v21, s[20:21] offset:48
	s_mul_i32 s17, s4, 1
	s_add_i32 s17, s17, s3
	s_min_u32 s17, s17, 0x1fff
	s_and_b32 s0, s17, 0x7ff
	s_lshl_b32 s0, s0, 8
	s_add_u32 s20, s18, s0
	s_addc_u32 s21, s19, 0
	global_load_dwordx4 v[92:95], v21, s[20:21]
	global_load_dwordx4 v[96:99], v21, s[20:21] offset:16
	global_load_dwordx4 v[100:103], v21, s[20:21] offset:32
	global_load_dwordx4 v[104:107], v21, s[20:21] offset:48
	s_waitcnt vmcnt(0)
	s_branch .Lpa_lat_b0
.Lpa_lat_entry1:
	s_cmpk_lt_u32 s3, 0x2000
	s_cbranch_scc0 .Lpa_done
	s_and_b32 s0, s3, 0x7ff
	s_lshl_b32 s0, s0, 8
	s_add_u32 s20, s18, s0
	s_addc_u32 s21, s19, 0
	global_load_dwordx4 v[92:95], v21, s[20:21]
	global_load_dwordx4 v[96:99], v21, s[20:21] offset:16
	global_load_dwordx4 v[100:103], v21, s[20:21] offset:32
	global_load_dwordx4 v[104:107], v21, s[20:21] offset:48
	s_mul_i32 s17, s4, 1
	s_add_i32 s17, s17, s3
	s_min_u32 s17, s17, 0x1fff
	s_and_b32 s0, s17, 0x7ff
	s_lshl_b32 s0, s0, 8
	s_add_u32 s20, s18, s0
	s_addc_u32 s21, s19, 0
	global_load_dwordx4 v[40:43], v21, s[20:21]
	global_load_dwordx4 v[44:47], v21, s[20:21] offset:16
	global_load_dwordx4 v[48:51], v21, s[20:21] offset:32
	global_load_dwordx4 v[52:55], v21, s[20:21] offset:48
	s_waitcnt vmcnt(0)
	s_branch .Lpa_lat_b1

.Lpa_lat_t0:
	s_waitcnt vmcnt(19)
.Lpa_lat_b0:
	v_lshlrev_b32_e32 v32, 16, v24
	v_and_b32_e32 v33, s85, v24
	v_lshlrev_b32_e32 v34, 16, v25
	v_and_b32_e32 v35, s85, v25
	v_lshlrev_b32_e32 v36, 16, v26
	v_and_b32_e32 v37, s85, v26
	v_lshlrev_b32_e32 v38, 16, v27
	v_and_b32_e32 v39, s85, v27
	s_mov_b64 exec, s[6:7]
	v_lshlrev_b32_e32 v66, 16, v28
	v_and_b32_e32 v67, s85, v28
	v_add_f32_e32 v32, v32, v66
	v_add_f32_e32 v33, v33, v67
	v_lshlrev_b32_e32 v66, 16, v29
	v_and_b32_e32 v67, s85, v29
	v_add_f32_e32 v34, v34, v66
	v_add_f32_e32 v35, v35, v67
	v_lshlrev_b32_e32 v66, 16, v30
	v_and_b32_e32 v67, s85, v30
	v_add_f32_e32 v36, v36, v66
	v_add_f32_e32 v37, v37, v67
	v_lshlrev_b32_e32 v66, 16, v31
	v_and_b32_e32 v67, s85, v31
	v_add_f32_e32 v38, v38, v66
	v_add_f32_e32 v39, v39, v67
	s_mov_b64 exec, -1
	s_mul_i32 s17, s4, 3
	s_add_i32 s17, s17, s3
	s_min_u32 s17, s17, 0x1fff
	v_mad_u64_u32 v[56:57], s[26:27], s17, v4, v[2:3]
	v_mov_b32_e32 v66, 0
	v_add_co_u32_e32 v60, vcc, v56, v5
	s_nop 1
	v_addc_co_u32_e32 v61, vcc, v57, v66, vcc
	global_load_dwordx4 v[88:91], v[60:61], off
	global_load_dwordx4 v[84:87], v[56:57], off
	v_mul_f32_e32 v66, v32, v32
	v_fmac_f32_e32 v66, v33, v33
	v_fmac_f32_e32 v66, v34, v34
	v_fmac_f32_e32 v66, v35, v35
	v_fmac_f32_e32 v66, v36, v36
	v_fmac_f32_e32 v66, v37, v37
	v_fmac_f32_e32 v66, v38, v38
	v_fmac_f32_e32 v66, v39, v39
	s_nop 1
	v_add_f32_dpp v66, v66, v66 quad_perm:[1,0,3,2] row_mask:0xf bank_mask:0xf
	s_nop 1
	v_add_f32_dpp v66, v66, v66 quad_perm:[2,3,0,1] row_mask:0xf bank_mask:0xf
	s_nop 1
	v_add_f32_dpp v66, v66, v66 row_half_mirror row_mask:0xf bank_mask:0xf
	v_mov_b32_e32 v67, 0x358637bd
	v_fmac_f32_e32 v67, s16, v66
	v_rsq_f32_e32 v67, v67
	s_mov_b64 exec, s[8:9]
	v_mul_f32_e32 v32, v32, v67
	v_mul_f32_e32 v33, v33, v67
	v_mul_f32_e32 v34, v34, v67
	v_mul_f32_e32 v35, v35, v67
	v_mul_f32_e32 v36, v36, v67
	v_mul_f32_e32 v37, v37, v67
	v_mul_f32_e32 v38, v38, v67
	v_mul_f32_e32 v39, v39, v67
	v_mul_f32_e32 v32, v32, v6
	v_mul_f32_e32 v33, v33, v7
	v_mul_f32_e32 v34, v34, v8
	v_mul_f32_e32 v35, v35, v9
	v_mul_f32_e32 v36, v36, v10
	v_mul_f32_e32 v37, v37, v11
	v_mul_f32_e32 v38, v38, v12
	v_mul_f32_e32 v39, v39, v13
	s_mov_b64 exec, -1
	s_waitcnt vmcnt(10)
	s_mov_b64 exec, s[14:15]
	s_cbranch_execz .Lpa_norope0
	v_xor_b32_e32 v41, v22, v41
	v_xor_b32_e32 v43, v22, v43
	v_xor_b32_e32 v45, v22, v45
	v_xor_b32_e32 v47, v22, v47
	v_xor_b32_e32 v49, v22, v49
	v_xor_b32_e32 v51, v22, v51
	v_xor_b32_e32 v53, v22, v53
	v_xor_b32_e32 v55, v22, v55
	v_mov_b32_dpp v66, v32 quad_perm:[2,3,0,1] row_mask:0xf bank_mask:0xf
	v_mul_f32_e32 v32, v32, v40
	s_nop 0
	v_fmac_f32_e32 v32, v66, v41
	v_mov_b32_dpp v66, v33 quad_perm:[2,3,0,1] row_mask:0xf bank_mask:0xf
	v_mul_f32_e32 v33, v33, v42
	s_nop 0
	v_fmac_f32_e32 v33, v66, v43
	v_mov_b32_dpp v66, v34 quad_perm:[2,3,0,1] row_mask:0xf bank_mask:0xf
	v_mul_f32_e32 v34, v34, v44
	s_nop 0
	v_fmac_f32_e32 v34, v66, v45
	v_mov_b32_dpp v66, v35 quad_perm:[2,3,0,1] row_mask:0xf bank_mask:0xf
	v_mul_f32_e32 v35, v35, v46
	s_nop 0
	v_fmac_f32_e32 v35, v66, v47
	v_mov_b32_dpp v66, v36 quad_perm:[2,3,0,1] row_mask:0xf bank_mask:0xf
	v_mul_f32_e32 v36, v36, v48
	s_nop 0
	v_fmac_f32_e32 v36, v66, v49
	v_mov_b32_dpp v66, v37 quad_perm:[2,3,0,1] row_mask:0xf bank_mask:0xf
	v_mul_f32_e32 v37, v37, v50
	s_nop 0
	v_fmac_f32_e32 v37, v66, v51
	v_mov_b32_dpp v66, v38 quad_perm:[2,3,0,1] row_mask:0xf bank_mask:0xf
	v_mul_f32_e32 v38, v38, v52
	s_nop 0
	v_fmac_f32_e32 v38, v66, v53
	v_mov_b32_dpp v66, v39 quad_perm:[2,3,0,1] row_mask:0xf bank_mask:0xf
	v_mul_f32_e32 v39, v39, v54
	s_nop 0
	v_fmac_f32_e32 v39, v66, v55
.Lpa_norope0:
	s_mov_b64 exec, -1
	s_mul_i32 s17, s4, 2
	s_add_i32 s17, s17, s3
	s_min_u32 s17, s17, 0x1fff
	s_and_b32 s0, s17, 0x7ff
	s_lshl_b32 s0, s0, 8
	s_add_u32 s20, s18, s0
	s_addc_u32 s21, s19, 0
	global_load_dwordx4 v[40:43], v21, s[20:21]
	global_load_dwordx4 v[44:47], v21, s[20:21] offset:16
	global_load_dwordx4 v[48:51], v21, s[20:21] offset:32
	global_load_dwordx4 v[52:55], v21, s[20:21] offset:48
	v_mul_f32_e32 v32, v32, v17
	v_mul_f32_e32 v33, v33, v17
	v_mul_f32_e32 v34, v34, v17
	v_mul_f32_e32 v35, v35, v17
	v_mul_f32_e32 v36, v36, v17
	v_mul_f32_e32 v37, v37, v17
	v_mul_f32_e32 v38, v38, v17
	v_mul_f32_e32 v39, v39, v17
	v_cvt_pk_bf16_f32 v62, v32, v33
	v_cvt_pk_bf16_f32 v63, v34, v35
	v_cvt_pk_bf16_f32 v64, v36, v37
	v_cvt_pk_bf16_f32 v65, v38, v39
	v_mad_u64_u32 v[56:57], s[26:27], s3, v16, v[14:15]
	s_mov_b64 exec, s[12:13]
	global_store_dwordx4 v[56:57], v[62:65], off
	s_mov_b64 exec, -1
	s_add_i32 s3, s3, s4
	s_cmpk_lt_u32 s3, 0x2000
	s_cbranch_scc0 .Lpa_done

.Lpa_lat_b1:
	v_lshlrev_b32_e32 v32, 16, v68
	v_and_b32_e32 v33, s85, v68
	v_lshlrev_b32_e32 v34, 16, v69
	v_and_b32_e32 v35, s85, v69
	v_lshlrev_b32_e32 v36, 16, v70
	v_and_b32_e32 v37, s85, v70
	v_lshlrev_b32_e32 v38, 16, v71
	v_and_b32_e32 v39, s85, v71
	s_mov_b64 exec, s[6:7]
	v_lshlrev_b32_e32 v66, 16, v72
	v_and_b32_e32 v67, s85, v72
	v_add_f32_e32 v32, v32, v66
	v_add_f32_e32 v33, v33, v67
	v_lshlrev_b32_e32 v66, 16, v73
	v_and_b32_e32 v67, s85, v73
	v_add_f32_e32 v34, v34, v66
	v_add_f32_e32 v35, v35, v67
	v_lshlrev_b32_e32 v66, 16, v74
	v_and_b32_e32 v67, s85, v74
	v_add_f32_e32 v36, v36, v66
	v_add_f32_e32 v37, v37, v67
	v_lshlrev_b32_e32 v66, 16, v75
	v_and_b32_e32 v67, s85, v75
	v_add_f32_e32 v38, v38, v66
	v_add_f32_e32 v39, v39, v67
	s_mov_b64 exec, -1
	s_mul_i32 s17, s4, 3
	s_add_i32 s17, s17, s3
	s_min_u32 s17, s17, 0x1fff
	v_mad_u64_u32 v[56:57], s[26:27], s17, v4, v[2:3]
	v_mov_b32_e32 v66, 0
	v_add_co_u32_e32 v60, vcc, v56, v5
	s_nop 1
	v_addc_co_u32_e32 v61, vcc, v57, v66, vcc
	global_load_dwordx4 v[28:31], v[60:61], off
	global_load_dwordx4 v[24:27], v[56:57], off
	v_mul_f32_e32 v66, v32, v32
	v_fmac_f32_e32 v66, v33, v33
	v_fmac_f32_e32 v66, v34, v34
	v_fmac_f32_e32 v66, v35, v35
	v_fmac_f32_e32 v66, v36, v36
	v_fmac_f32_e32 v66, v37, v37
	v_fmac_f32_e32 v66, v38, v38
	v_fmac_f32_e32 v66, v39, v39
	s_nop 1
	v_add_f32_dpp v66, v66, v66 quad_perm:[1,0,3,2] row_mask:0xf bank_mask:0xf
	s_nop 1
	v_add_f32_dpp v66, v66, v66 quad_perm:[2,3,0,1] row_mask:0xf bank_mask:0xf
	s_nop 1
	v_add_f32_dpp v66, v66, v66 row_half_mirror row_mask:0xf bank_mask:0xf
	v_mov_b32_e32 v67, 0x358637bd
	v_fmac_f32_e32 v67, s16, v66
	v_rsq_f32_e32 v67, v67
	s_mov_b64 exec, s[8:9]
	v_mul_f32_e32 v32, v32, v67
	v_mul_f32_e32 v33, v33, v67
	v_mul_f32_e32 v34, v34, v67
	v_mul_f32_e32 v35, v35, v67
	v_mul_f32_e32 v36, v36, v67
	v_mul_f32_e32 v37, v37, v67
	v_mul_f32_e32 v38, v38, v67
	v_mul_f32_e32 v39, v39, v67
	v_mul_f32_e32 v32, v32, v6
	v_mul_f32_e32 v33, v33, v7
	v_mul_f32_e32 v34, v34, v8
	v_mul_f32_e32 v35, v35, v9
	v_mul_f32_e32 v36, v36, v10
	v_mul_f32_e32 v37, v37, v11
	v_mul_f32_e32 v38, v38, v12
	v_mul_f32_e32 v39, v39, v13
	s_mov_b64 exec, -1
	s_waitcnt vmcnt(10)
	s_mov_b64 exec, s[14:15]
	s_cbranch_execz .Lpa_norope1
	v_xor_b32_e32 v93, v22, v93
	v_xor_b32_e32 v95, v22, v95
	v_xor_b32_e32 v97, v22, v97
	v_xor_b32_e32 v99, v22, v99
	v_xor_b32_e32 v101, v22, v101
	v_xor_b32_e32 v103, v22, v103
	v_xor_b32_e32 v105, v22, v105
	v_xor_b32_e32 v107, v22, v107
	v_mov_b32_dpp v66, v32 quad_perm:[2,3,0,1] row_mask:0xf bank_mask:0xf
	v_mul_f32_e32 v32, v32, v92
	s_nop 0
	v_fmac_f32_e32 v32, v66, v93
	v_mov_b32_dpp v66, v33 quad_perm:[2,3,0,1] row_mask:0xf bank_mask:0xf
	v_mul_f32_e32 v33, v33, v94
	s_nop 0
	v_fmac_f32_e32 v33, v66, v95
	v_mov_b32_dpp v66, v34 quad_perm:[2,3,0,1] row_mask:0xf bank_mask:0xf
	v_mul_f32_e32 v34, v34, v96
	s_nop 0
	v_fmac_f32_e32 v34, v66, v97
	v_mov_b32_dpp v66, v35 quad_perm:[2,3,0,1] row_mask:0xf bank_mask:0xf
	v_mul_f32_e32 v35, v35, v98
	s_nop 0
	v_fmac_f32_e32 v35, v66, v99
	v_mov_b32_dpp v66, v36 quad_perm:[2,3,0,1] row_mask:0xf bank_mask:0xf
	v_mul_f32_e32 v36, v36, v100
	s_nop 0
	v_fmac_f32_e32 v36, v66, v101
	v_mov_b32_dpp v66, v37 quad_perm:[2,3,0,1] row_mask:0xf bank_mask:0xf
	v_mul_f32_e32 v37, v37, v102
	s_nop 0
	v_fmac_f32_e32 v37, v66, v103
	v_mov_b32_dpp v66, v38 quad_perm:[2,3,0,1] row_mask:0xf bank_mask:0xf
	v_mul_f32_e32 v38, v38, v104
	s_nop 0
	v_fmac_f32_e32 v38, v66, v105
	v_mov_b32_dpp v66, v39 quad_perm:[2,3,0,1] row_mask:0xf bank_mask:0xf
	v_mul_f32_e32 v39, v39, v106
	s_nop 0
	v_fmac_f32_e32 v39, v66, v107
.Lpa_norope1:
	s_mov_b64 exec, -1
	s_mul_i32 s17, s4, 2
	s_add_i32 s17, s17, s3
	s_min_u32 s17, s17, 0x1fff
	s_and_b32 s0, s17, 0x7ff
	s_lshl_b32 s0, s0, 8
	s_add_u32 s20, s18, s0
	s_addc_u32 s21, s19, 0
	global_load_dwordx4 v[92:95], v21, s[20:21]
	global_load_dwordx4 v[96:99], v21, s[20:21] offset:16
	global_load_dwordx4 v[100:103], v21, s[20:21] offset:32
	global_load_dwordx4 v[104:107], v21, s[20:21] offset:48
	v_mul_f32_e32 v32, v32, v17
	v_mul_f32_e32 v33, v33, v17
	v_mul_f32_e32 v34, v34, v17
	v_mul_f32_e32 v35, v35, v17
	v_mul_f32_e32 v36, v36, v17
	v_mul_f32_e32 v37, v37, v17
	v_mul_f32_e32 v38, v38, v17
	v_mul_f32_e32 v39, v39, v17
	v_cvt_pk_bf16_f32 v62, v32, v33
	v_cvt_pk_bf16_f32 v63, v34, v35
	v_cvt_pk_bf16_f32 v64, v36, v37
	v_cvt_pk_bf16_f32 v65, v38, v39
	v_mad_u64_u32 v[56:57], s[26:27], s3, v16, v[14:15]
	s_mov_b64 exec, s[12:13]
	global_store_dwordx4 v[56:57], v[62:65], off
	s_mov_b64 exec, -1
	s_add_i32 s3, s3, s4
	s_cmpk_lt_u32 s3, 0x2000
	s_cbranch_scc0 .Lpa_done

.Lpa_lat_b2:
	v_lshlrev_b32_e32 v32, 16, v76
	v_and_b32_e32 v33, s85, v76
	v_lshlrev_b32_e32 v34, 16, v77
	v_and_b32_e32 v35, s85, v77
	v_lshlrev_b32_e32 v36, 16, v78
	v_and_b32_e32 v37, s85, v78
	v_lshlrev_b32_e32 v38, 16, v79
	v_and_b32_e32 v39, s85, v79
	s_mov_b64 exec, s[6:7]
	v_lshlrev_b32_e32 v66, 16, v80
	v_and_b32_e32 v67, s85, v80
	v_add_f32_e32 v32, v32, v66
	v_add_f32_e32 v33, v33, v67
	v_lshlrev_b32_e32 v66, 16, v81
	v_and_b32_e32 v67, s85, v81
	v_add_f32_e32 v34, v34, v66
	v_add_f32_e32 v35, v35, v67
	v_lshlrev_b32_e32 v66, 16, v82
	v_and_b32_e32 v67, s85, v82
	v_add_f32_e32 v36, v36, v66
	v_add_f32_e32 v37, v37, v67
	v_lshlrev_b32_e32 v66, 16, v83
	v_and_b32_e32 v67, s85, v83
	v_add_f32_e32 v38, v38, v66
	v_add_f32_e32 v39, v39, v67
	s_mov_b64 exec, -1
	s_mul_i32 s17, s4, 3
	s_add_i32 s17, s17, s3
	s_min_u32 s17, s17, 0x1fff
	v_mad_u64_u32 v[56:57], s[26:27], s17, v4, v[2:3]
	v_mov_b32_e32 v66, 0
	v_add_co_u32_e32 v60, vcc, v56, v5
	s_nop 1
	v_addc_co_u32_e32 v61, vcc, v57, v66, vcc
	global_load_dwordx4 v[72:75], v[60:61], off
	global_load_dwordx4 v[68:71], v[56:57], off
	v_mul_f32_e32 v66, v32, v32
	v_fmac_f32_e32 v66, v33, v33
	v_fmac_f32_e32 v66, v34, v34
	v_fmac_f32_e32 v66, v35, v35
	v_fmac_f32_e32 v66, v36, v36
	v_fmac_f32_e32 v66, v37, v37
	v_fmac_f32_e32 v66, v38, v38
	v_fmac_f32_e32 v66, v39, v39
	s_nop 1
	v_add_f32_dpp v66, v66, v66 quad_perm:[1,0,3,2] row_mask:0xf bank_mask:0xf
	s_nop 1
	v_add_f32_dpp v66, v66, v66 quad_perm:[2,3,0,1] row_mask:0xf bank_mask:0xf
	s_nop 1
	v_add_f32_dpp v66, v66, v66 row_half_mirror row_mask:0xf bank_mask:0xf
	v_mov_b32_e32 v67, 0x358637bd
	v_fmac_f32_e32 v67, s16, v66
	v_rsq_f32_e32 v67, v67
	s_mov_b64 exec, s[8:9]
	v_mul_f32_e32 v32, v32, v67
	v_mul_f32_e32 v33, v33, v67
	v_mul_f32_e32 v34, v34, v67
	v_mul_f32_e32 v35, v35, v67
	v_mul_f32_e32 v36, v36, v67
	v_mul_f32_e32 v37, v37, v67
	v_mul_f32_e32 v38, v38, v67
	v_mul_f32_e32 v39, v39, v67
	v_mul_f32_e32 v32, v32, v6
	v_mul_f32_e32 v33, v33, v7
	v_mul_f32_e32 v34, v34, v8
	v_mul_f32_e32 v35, v35, v9
	v_mul_f32_e32 v36, v36, v10
	v_mul_f32_e32 v37, v37, v11
	v_mul_f32_e32 v38, v38, v12
	v_mul_f32_e32 v39, v39, v13
	s_mov_b64 exec, -1
	s_waitcnt vmcnt(10)
	s_mov_b64 exec, s[14:15]
	s_cbranch_execz .Lpa_norope2
	v_xor_b32_e32 v41, v22, v41
	v_xor_b32_e32 v43, v22, v43
	v_xor_b32_e32 v45, v22, v45
	v_xor_b32_e32 v47, v22, v47
	v_xor_b32_e32 v49, v22, v49
	v_xor_b32_e32 v51, v22, v51
	v_xor_b32_e32 v53, v22, v53
	v_xor_b32_e32 v55, v22, v55
	v_mov_b32_dpp v66, v32 quad_perm:[2,3,0,1] row_mask:0xf bank_mask:0xf
	v_mul_f32_e32 v32, v32, v40
	s_nop 0
	v_fmac_f32_e32 v32, v66, v41
	v_mov_b32_dpp v66, v33 quad_perm:[2,3,0,1] row_mask:0xf bank_mask:0xf
	v_mul_f32_e32 v33, v33, v42
	s_nop 0
	v_fmac_f32_e32 v33, v66, v43
	v_mov_b32_dpp v66, v34 quad_perm:[2,3,0,1] row_mask:0xf bank_mask:0xf
	v_mul_f32_e32 v34, v34, v44
	s_nop 0
	v_fmac_f32_e32 v34, v66, v45
	v_mov_b32_dpp v66, v35 quad_perm:[2,3,0,1] row_mask:0xf bank_mask:0xf
	v_mul_f32_e32 v35, v35, v46
	s_nop 0
	v_fmac_f32_e32 v35, v66, v47
	v_mov_b32_dpp v66, v36 quad_perm:[2,3,0,1] row_mask:0xf bank_mask:0xf
	v_mul_f32_e32 v36, v36, v48
	s_nop 0
	v_fmac_f32_e32 v36, v66, v49
	v_mov_b32_dpp v66, v37 quad_perm:[2,3,0,1] row_mask:0xf bank_mask:0xf
	v_mul_f32_e32 v37, v37, v50
	s_nop 0
	v_fmac_f32_e32 v37, v66, v51
	v_mov_b32_dpp v66, v38 quad_perm:[2,3,0,1] row_mask:0xf bank_mask:0xf
	v_mul_f32_e32 v38, v38, v52
	s_nop 0
	v_fmac_f32_e32 v38, v66, v53
	v_mov_b32_dpp v66, v39 quad_perm:[2,3,0,1] row_mask:0xf bank_mask:0xf
	v_mul_f32_e32 v39, v39, v54
	s_nop 0
	v_fmac_f32_e32 v39, v66, v55

.Lpa_lat_b3:
	v_lshlrev_b32_e32 v32, 16, v84
	v_and_b32_e32 v33, s85, v84
	v_lshlrev_b32_e32 v34, 16, v85
	v_and_b32_e32 v35, s85, v85
	v_lshlrev_b32_e32 v36, 16, v86
	v_and_b32_e32 v37, s85, v86
	v_lshlrev_b32_e32 v38, 16, v87
	v_and_b32_e32 v39, s85, v87
	s_mov_b64 exec, s[6:7]
	v_lshlrev_b32_e32 v66, 16, v88
	v_and_b32_e32 v67, s85, v88
	v_add_f32_e32 v32, v32, v66
	v_add_f32_e32 v33, v33, v67
	v_lshlrev_b32_e32 v66, 16, v89
	v_and_b32_e32 v67, s85, v89
	v_add_f32_e32 v34, v34, v66
	v_add_f32_e32 v35, v35, v67
	v_lshlrev_b32_e32 v66, 16, v90
	v_and_b32_e32 v67, s85, v90
	v_add_f32_e32 v36, v36, v66
	v_add_f32_e32 v37, v37, v67
	v_lshlrev_b32_e32 v66, 16, v91
	v_and_b32_e32 v67, s85, v91
	v_add_f32_e32 v38, v38, v66
	v_add_f32_e32 v39, v39, v67
	s_mov_b64 exec, -1
	s_mul_i32 s17, s4, 3
	s_add_i32 s17, s17, s3
	s_min_u32 s17, s17, 0x1fff
	v_mad_u64_u32 v[56:57], s[26:27], s17, v4, v[2:3]
	v_mov_b32_e32 v66, 0
	v_add_co_u32_e32 v60, vcc, v56, v5
	s_nop 1
	v_addc_co_u32_e32 v61, vcc, v57, v66, vcc
	global_load_dwordx4 v[80:83], v[60:61], off
	global_load_dwordx4 v[76:79], v[56:57], off
	v_mul_f32_e32 v66, v32, v32
	v_fmac_f32_e32 v66, v33, v33
	v_fmac_f32_e32 v66, v34, v34
	v_fmac_f32_e32 v66, v35, v35
	v_fmac_f32_e32 v66, v36, v36
	v_fmac_f32_e32 v66, v37, v37
	v_fmac_f32_e32 v66, v38, v38
	v_fmac_f32_e32 v66, v39, v39
	s_nop 1
	v_add_f32_dpp v66, v66, v66 quad_perm:[1,0,3,2] row_mask:0xf bank_mask:0xf
	s_nop 1
	v_add_f32_dpp v66, v66, v66 quad_perm:[2,3,0,1] row_mask:0xf bank_mask:0xf
	s_nop 1
	v_add_f32_dpp v66, v66, v66 row_half_mirror row_mask:0xf bank_mask:0xf
	v_mov_b32_e32 v67, 0x358637bd
	v_fmac_f32_e32 v67, s16, v66
	v_rsq_f32_e32 v67, v67
	s_mov_b64 exec, s[8:9]
	v_mul_f32_e32 v32, v32, v67
	v_mul_f32_e32 v33, v33, v67
	v_mul_f32_e32 v34, v34, v67
	v_mul_f32_e32 v35, v35, v67
	v_mul_f32_e32 v36, v36, v67
	v_mul_f32_e32 v37, v37, v67
	v_mul_f32_e32 v38, v38, v67
	v_mul_f32_e32 v39, v39, v67
	v_mul_f32_e32 v32, v32, v6
	v_mul_f32_e32 v33, v33, v7
	v_mul_f32_e32 v34, v34, v8
	v_mul_f32_e32 v35, v35, v9
	v_mul_f32_e32 v36, v36, v10
	v_mul_f32_e32 v37, v37, v11
	v_mul_f32_e32 v38, v38, v12
	v_mul_f32_e32 v39, v39, v13
	s_mov_b64 exec, -1
	s_waitcnt vmcnt(10)
	s_mov_b64 exec, s[14:15]
	s_cbranch_execz .Lpa_norope3
	v_xor_b32_e32 v93, v22, v93
	v_xor_b32_e32 v95, v22, v95
	v_xor_b32_e32 v97, v22, v97
	v_xor_b32_e32 v99, v22, v99
	v_xor_b32_e32 v101, v22, v101
	v_xor_b32_e32 v103, v22, v103
	v_xor_b32_e32 v105, v22, v105
	v_xor_b32_e32 v107, v22, v107
	v_mov_b32_dpp v66, v32 quad_perm:[2,3,0,1] row_mask:0xf bank_mask:0xf
	v_mul_f32_e32 v32, v32, v92
	s_nop 0
	v_fmac_f32_e32 v32, v66, v93
	v_mov_b32_dpp v66, v33 quad_perm:[2,3,0,1] row_mask:0xf bank_mask:0xf
	v_mul_f32_e32 v33, v33, v94
	s_nop 0
	v_fmac_f32_e32 v33, v66, v95
	v_mov_b32_dpp v66, v34 quad_perm:[2,3,0,1] row_mask:0xf bank_mask:0xf
	v_mul_f32_e32 v34, v34, v96
	s_nop 0
	v_fmac_f32_e32 v34, v66, v97
	v_mov_b32_dpp v66, v35 quad_perm:[2,3,0,1] row_mask:0xf bank_mask:0xf
	v_mul_f32_e32 v35, v35, v98
	s_nop 0
	v_fmac_f32_e32 v35, v66, v99
	v_mov_b32_dpp v66, v36 quad_perm:[2,3,0,1] row_mask:0xf bank_mask:0xf
	v_mul_f32_e32 v36, v36, v100
	s_nop 0
	v_fmac_f32_e32 v36, v66, v101
	v_mov_b32_dpp v66, v37 quad_perm:[2,3,0,1] row_mask:0xf bank_mask:0xf
	v_mul_f32_e32 v37, v37, v102
	s_nop 0
	v_fmac_f32_e32 v37, v66, v103
	v_mov_b32_dpp v66, v38 quad_perm:[2,3,0,1] row_mask:0xf bank_mask:0xf
	v_mul_f32_e32 v38, v38, v104
	s_nop 0
	v_fmac_f32_e32 v38, v66, v105
	v_mov_b32_dpp v66, v39 quad_perm:[2,3,0,1] row_mask:0xf bank_mask:0xf
	v_mul_f32_e32 v39, v39, v106
	s_nop 0
	v_fmac_f32_e32 v39, v66, v107
.Lpa_norope3:
	s_mov_b64 exec, -1
	s_mul_i32 s17, s4, 2
	s_add_i32 s17, s17, s3
	s_min_u32 s17, s17, 0x1fff
	s_and_b32 s0, s17, 0x7ff
	s_lshl_b32 s0, s0, 8
	s_add_u32 s20, s18, s0
	s_addc_u32 s21, s19, 0
	global_load_dwordx4 v[92:95], v21, s[20:21]
	global_load_dwordx4 v[96:99], v21, s[20:21] offset:16
	global_load_dwordx4 v[100:103], v21, s[20:21] offset:32
	global_load_dwordx4 v[104:107], v21, s[20:21] offset:48
	v_mul_f32_e32 v32, v32, v17
	v_mul_f32_e32 v33, v33, v17
	v_mul_f32_e32 v34, v34, v17
	v_mul_f32_e32 v35, v35, v17
	v_mul_f32_e32 v36, v36, v17
	v_mul_f32_e32 v37, v37, v17
	v_mul_f32_e32 v38, v38, v17
	v_mul_f32_e32 v39, v39, v17
	v_cvt_pk_bf16_f32 v62, v32, v33
	v_cvt_pk_bf16_f32 v63, v34, v35
	v_cvt_pk_bf16_f32 v64, v36, v37
	v_cvt_pk_bf16_f32 v65, v38, v39
	v_mad_u64_u32 v[56:57], s[26:27], s3, v16, v[14:15]
	s_mov_b64 exec, s[12:13]
	global_store_dwordx4 v[56:57], v[62:65], off
	s_mov_b64 exec, -1
	s_add_i32 s3, s3, s4
	s_cmpk_lt_u32 s3, 0x2000
	s_cbranch_scc1 .Lpa_lat_t0
